# adds EpiUp epilogue: row-sum + rope-table loads prefetched (non-rope and rope branches), counted waits
# baseline (speedup 1.0000x reference)
_Z10fwd_kernel4Args:
	s_mov_b32 s100, 0
	s_mov_b32 s92, s2
	s_load_dword s87, s[0:1], 0xe0
	s_load_dwordx2 s[28:29], s[0:1], 0xd0
	s_load_dwordx4 s[8:11], s[0:1], 0xc0
	s_add_u32 s2, s0, 0xe0
	s_addc_u32 s3, s1, 0
	v_writelane_b32 v250, s2, 0
	s_nop 1
	v_writelane_b32 v250, s3, 1
	s_waitcnt lgkmcnt(0)
	s_and_b32 s2, s87, 7
	s_cmp_lg_u32 s2, 0
	v_writelane_b32 v250, s92, 2
	s_cbranch_scc0 .LBB0_140
	v_cmp_gt_u32_e32 vcc, 64, v0
	s_and_saveexec_b64 s[2:3], vcc

.LBB0_551:
	s_lshl_b32 s0, s22, 8
	s_add_i32 s0, s0, s72
	s_cmp_ge_i32 s20, s41
	s_cselect_b64 s[24:25], -1, 0
	v_mbcnt_lo_u32_b32 v0, -1, 0
	v_mbcnt_hi_u32_b32 v0, -1, v0
	s_nop 0
	v_and_or_b32 v130, v0, 15, s0
	s_and_b64 s[0:1], s[24:25], exec
	s_cselect_b32 s0, s41, 0
	s_cselect_b32 s1, s40, 0x18000
	s_sub_i32 s0, s20, s0
	s_lshl_b32 s1, s1, 3
	s_add_u32 s22, s56, s1
	s_addc_u32 s23, s57, 0
	s_cmp_gt_i32 s0, 7
	s_cselect_b64 s[26:27], -1, 0
	s_and_b64 s[28:29], s[24:25], s[26:27]
	v_or_b32_e32 v138, 16, v130
	v_or_b32_e32 v136, 32, v130
	v_or_b32_e32 v134, 48, v130
	v_bfe_u32 v144, v0, 4, 2
	s_mov_b64 s[26:27], -1
	s_and_b64 vcc, exec, s[28:29]
	v_ashrrev_i32_e32 v131, 31, v130
	v_ashrrev_i32_e32 v139, 31, v138
	v_ashrrev_i32_e32 v137, 31, v136
	v_ashrrev_i32_e32 v135, 31, v134
	s_cbranch_vccnz .LBB0_554
	v_lshl_add_u64 v[132:133], v[130:131], 3, s[22:23]
	global_load_dwordx2 v[140:141], v[132:133], off
	global_load_dwordx2 v[164:165], v[132:133], off offset:128
	global_load_dwordx2 v[166:167], v[132:133], off offset:256
	global_load_dwordx2 v[168:169], v[132:133], off offset:384
	global_load_dwordx2 v[170:171], v[132:133], off offset:1024
	global_load_dwordx2 v[172:173], v[132:133], off offset:1152
	global_load_dwordx2 v[174:175], v[132:133], off offset:1280
	global_load_dwordx2 v[176:177], v[132:133], off offset:1408
	s_cmp_lt_i32 s0, 8
	s_mov_b32 s1, 0x1b700000
	s_cselect_b32 s1, s1, 0x1f700000
	s_and_b64 s[24:25], s[24:25], exec
	s_cselect_b32 s1, 0x25900000, s1
	s_add_u32 s24, s6, s1
	s_addc_u32 s25, s7, 0
	s_lshl_b32 s1, s20, 8
	s_and_b32 s1, s1, 0x700
	v_lshl_or_b32 v0, v144, 3, s1
	v_readlane_b32 s1, v255, 26
	s_mov_b64 s[20:21], 0x80000
	s_nop 0
	v_or_b32_e32 v0, s1, v0
	v_lshlrev_b32_e32 v0, 1, v0
	v_lshl_add_u64 v[142:143], s[24:25], 0, v[0:1]
	s_mov_b32 s1, 0x80000
	s_waitcnt vmcnt(0)
	v_xor_b32_e32 v0, v140, v141
	v_ashrrev_i32_e32 v0, 31, v0
	v_ffbh_i32_e32 v145, v141
	v_add_u32_e32 v0, 32, v0
	v_add_u32_e32 v145, -1, v145
	v_min_u32_e32 v0, v145, v0
	v_lshlrev_b64 v[140:141], v0, v[140:141]
	v_min_u32_e32 v140, 1, v140
	v_or_b32_e32 v140, v141, v140
	v_cvt_f32_i32_e32 v140, v140
	v_sub_u32_e32 v0, 32, v0
	v_ldexp_f32 v0, v140, v0
	v_mul_f32_e32 v0, 0x35800000, v0
	v_fmamk_f32 v0, v0, 0x3b000000, v180
	v_cmp_gt_f32_e32 vcc, s73, v0
	v_mul_f32_e32 v140, 0x4b800000, v0
	s_nop 0
	v_cndmask_b32_e32 v0, v0, v140, vcc
	v_rsq_f32_e32 v0, v0
	s_nop 0
	v_mul_f32_e32 v140, 0x45800000, v0
	v_cndmask_b32_e32 v0, v0, v140, vcc
	v_lshlrev_b64 v[140:141], 12, v[130:131]
	v_pk_mul_f32 v[154:155], v[124:125], v[0:1] op_sel_hi:[1,0]
	v_pk_mul_f32 v[152:153], v[122:123], v[0:1] op_sel_hi:[1,0]
	v_lshl_add_u64 v[140:141], v[142:143], 0, v[140:141]
	v_pk_mul_f32 v[156:157], v[116:117], v[0:1] op_sel_hi:[1,0]
	v_pk_mul_f32 v[158:159], v[114:115], v[0:1] op_sel_hi:[1,0]
	v_cvt_pk_bf16_f32 v152, v152, v153
	v_cvt_pk_bf16_f32 v153, v154, v155
	s_nop 0
	v_cvt_pk_bf16_f32 v154, v158, v159
	v_cvt_pk_bf16_f32 v155, v156, v157
	flat_store_dwordx4 v[140:141], v[152:155]
	v_pk_mul_f32 v[156:157], v[120:121], v[0:1] op_sel_hi:[1,0]
	v_pk_mul_f32 v[158:159], v[118:119], v[0:1] op_sel_hi:[1,0]
	v_pk_mul_f32 v[154:155], v[128:129], v[0:1] op_sel_hi:[1,0]
	v_pk_mul_f32 v[152:153], v[126:127], v[0:1] op_sel_hi:[1,0]
	s_nop 0
	v_cvt_pk_bf16_f32 v152, v152, v153
	v_cvt_pk_bf16_f32 v153, v154, v155
	v_cvt_pk_bf16_f32 v154, v158, v159
	v_cvt_pk_bf16_f32 v155, v156, v157
	flat_store_dwordx4 v[140:141], v[152:155] offset:256
	s_nop 1
	v_mov_b64_e32 v[152:153], v[164:165]
	v_xor_b32_e32 v0, v152, v153
	v_ashrrev_i32_e32 v0, 31, v0
	v_ffbh_i32_e32 v145, v153
	v_add_u32_e32 v0, 32, v0
	v_add_u32_e32 v145, -1, v145
	v_min_u32_e32 v0, v145, v0
	v_lshlrev_b64 v[152:153], v0, v[152:153]
	v_min_u32_e32 v145, 1, v152
	v_or_b32_e32 v145, v153, v145
	v_cvt_f32_i32_e32 v145, v145
	v_sub_u32_e32 v0, 32, v0
	v_lshlrev_b64 v[152:153], 12, v[138:139]
	v_lshl_add_u64 v[156:157], v[142:143], 0, v[152:153]
	v_ldexp_f32 v0, v145, v0
	v_mul_f32_e32 v0, 0x35800000, v0
	v_fmamk_f32 v0, v0, 0x3b000000, v180
	v_cmp_gt_f32_e32 vcc, s73, v0
	v_mul_f32_e32 v145, 0x4b800000, v0
	s_nop 0
	v_cndmask_b32_e32 v0, v0, v145, vcc
	v_rsq_f32_e32 v0, v0
	s_nop 0
	v_mul_f32_e32 v145, 0x45800000, v0
	v_cndmask_b32_e32 v0, v0, v145, vcc
	v_pk_mul_f32 v[154:155], v[108:109], v[0:1] op_sel_hi:[1,0]
	v_pk_mul_f32 v[152:153], v[106:107], v[0:1] op_sel_hi:[1,0]
	v_pk_mul_f32 v[158:159], v[100:101], v[0:1] op_sel_hi:[1,0]
	v_pk_mul_f32 v[160:161], v[98:99], v[0:1] op_sel_hi:[1,0]
	v_cvt_pk_bf16_f32 v152, v152, v153
	v_cvt_pk_bf16_f32 v153, v154, v155
	s_nop 0
	v_cvt_pk_bf16_f32 v154, v160, v161
	v_cvt_pk_bf16_f32 v155, v158, v159
	flat_store_dwordx4 v[156:157], v[152:155]
	v_pk_mul_f32 v[158:159], v[104:105], v[0:1] op_sel_hi:[1,0]
	v_pk_mul_f32 v[160:161], v[102:103], v[0:1] op_sel_hi:[1,0]
	v_pk_mul_f32 v[154:155], v[112:113], v[0:1] op_sel_hi:[1,0]
	v_pk_mul_f32 v[152:153], v[110:111], v[0:1] op_sel_hi:[1,0]
	s_nop 0
	v_cvt_pk_bf16_f32 v152, v152, v153
	v_cvt_pk_bf16_f32 v153, v154, v155
	v_cvt_pk_bf16_f32 v154, v160, v161
	v_cvt_pk_bf16_f32 v155, v158, v159
	flat_store_dwordx4 v[156:157], v[152:155] offset:256
	s_nop 1
	v_mov_b64_e32 v[152:153], v[166:167]
	v_xor_b32_e32 v0, v152, v153
	v_ashrrev_i32_e32 v0, 31, v0
	v_ffbh_i32_e32 v145, v153
	v_add_u32_e32 v0, 32, v0
	v_add_u32_e32 v145, -1, v145
	v_min_u32_e32 v0, v145, v0
	v_lshlrev_b64 v[152:153], v0, v[152:153]
	v_min_u32_e32 v145, 1, v152
	v_or_b32_e32 v145, v153, v145
	v_cvt_f32_i32_e32 v145, v145
	v_sub_u32_e32 v0, 32, v0
	v_lshlrev_b64 v[152:153], 12, v[136:137]
	v_lshl_add_u64 v[156:157], v[142:143], 0, v[152:153]
	v_ldexp_f32 v0, v145, v0
	v_mul_f32_e32 v0, 0x35800000, v0
	v_fmamk_f32 v0, v0, 0x3b000000, v180
	v_cmp_gt_f32_e32 vcc, s73, v0
	v_mul_f32_e32 v145, 0x4b800000, v0
	s_nop 0
	v_cndmask_b32_e32 v0, v0, v145, vcc
	v_rsq_f32_e32 v0, v0
	s_nop 0
	v_mul_f32_e32 v145, 0x45800000, v0
	v_cndmask_b32_e32 v0, v0, v145, vcc
	v_pk_mul_f32 v[154:155], v[92:93], v[0:1] op_sel_hi:[1,0]
	v_pk_mul_f32 v[152:153], v[90:91], v[0:1] op_sel_hi:[1,0]
	v_pk_mul_f32 v[158:159], v[84:85], v[0:1] op_sel_hi:[1,0]
	v_pk_mul_f32 v[160:161], v[82:83], v[0:1] op_sel_hi:[1,0]
	v_cvt_pk_bf16_f32 v152, v152, v153
	v_cvt_pk_bf16_f32 v153, v154, v155
	s_nop 0
	v_cvt_pk_bf16_f32 v154, v160, v161
	v_cvt_pk_bf16_f32 v155, v158, v159
	flat_store_dwordx4 v[156:157], v[152:155]
	v_pk_mul_f32 v[158:159], v[88:89], v[0:1] op_sel_hi:[1,0]
	v_pk_mul_f32 v[160:161], v[86:87], v[0:1] op_sel_hi:[1,0]
	v_pk_mul_f32 v[154:155], v[96:97], v[0:1] op_sel_hi:[1,0]
	v_pk_mul_f32 v[152:153], v[94:95], v[0:1] op_sel_hi:[1,0]
	s_nop 0
	v_cvt_pk_bf16_f32 v152, v152, v153
	v_cvt_pk_bf16_f32 v153, v154, v155
	v_cvt_pk_bf16_f32 v154, v160, v161
	v_cvt_pk_bf16_f32 v155, v158, v159
	flat_store_dwordx4 v[156:157], v[152:155] offset:256
	s_nop 1
	v_mov_b64_e32 v[152:153], v[168:169]
	v_xor_b32_e32 v0, v152, v153
	v_ashrrev_i32_e32 v0, 31, v0
	v_ffbh_i32_e32 v145, v153
	v_add_u32_e32 v0, 32, v0
	v_add_u32_e32 v145, -1, v145
	v_min_u32_e32 v0, v145, v0
	v_lshlrev_b64 v[152:153], v0, v[152:153]
	v_min_u32_e32 v145, 1, v152
	v_or_b32_e32 v145, v153, v145
	v_cvt_f32_i32_e32 v145, v145
	v_sub_u32_e32 v0, 32, v0
	v_lshlrev_b64 v[152:153], 12, v[134:135]
	v_lshl_add_u64 v[142:143], v[142:143], 0, v[152:153]
	v_ldexp_f32 v0, v145, v0
	v_mul_f32_e32 v0, 0x35800000, v0
	v_fmamk_f32 v0, v0, 0x3b000000, v180
	v_cmp_gt_f32_e32 vcc, s73, v0
	v_mul_f32_e32 v145, 0x4b800000, v0
	s_nop 0
	v_cndmask_b32_e32 v0, v0, v145, vcc
	v_rsq_f32_e32 v0, v0
	s_nop 0
	v_mul_f32_e32 v145, 0x45800000, v0
	v_cndmask_b32_e32 v0, v0, v145, vcc
	v_pk_mul_f32 v[154:155], v[76:77], v[0:1] op_sel_hi:[1,0]
	v_pk_mul_f32 v[152:153], v[74:75], v[0:1] op_sel_hi:[1,0]
	v_pk_mul_f32 v[156:157], v[68:69], v[0:1] op_sel_hi:[1,0]
	v_pk_mul_f32 v[158:159], v[66:67], v[0:1] op_sel_hi:[1,0]
	v_cvt_pk_bf16_f32 v152, v152, v153
	v_cvt_pk_bf16_f32 v153, v154, v155
	s_nop 0
	v_cvt_pk_bf16_f32 v154, v158, v159
	v_cvt_pk_bf16_f32 v155, v156, v157
	flat_store_dwordx4 v[142:143], v[152:155]
	v_pk_mul_f32 v[156:157], v[72:73], v[0:1] op_sel_hi:[1,0]
	v_pk_mul_f32 v[158:159], v[70:71], v[0:1] op_sel_hi:[1,0]
	v_pk_mul_f32 v[154:155], v[80:81], v[0:1] op_sel_hi:[1,0]
	v_pk_mul_f32 v[152:153], v[78:79], v[0:1] op_sel_hi:[1,0]
	s_nop 0
	v_cvt_pk_bf16_f32 v152, v152, v153
	v_cvt_pk_bf16_f32 v153, v154, v155
	v_cvt_pk_bf16_f32 v154, v158, v159
	v_cvt_pk_bf16_f32 v155, v156, v157
	flat_store_dwordx4 v[142:143], v[152:155] offset:256
	s_nop 1
	v_mov_b64_e32 v[142:143], v[170:171]
	v_xor_b32_e32 v0, v142, v143
	v_ashrrev_i32_e32 v0, 31, v0
	v_ffbh_i32_e32 v145, v143
	v_add_u32_e32 v0, 32, v0
	v_add_u32_e32 v145, -1, v145
	v_min_u32_e32 v0, v145, v0
	v_lshlrev_b64 v[142:143], v0, v[142:143]
	v_min_u32_e32 v142, 1, v142
	v_or_b32_e32 v142, v143, v142
	v_cvt_f32_i32_e32 v142, v142
	v_sub_u32_e32 v0, 32, v0
	v_ldexp_f32 v0, v142, v0
	v_mul_f32_e32 v0, 0x35800000, v0
	v_fmamk_f32 v0, v0, 0x3b000000, v180
	v_cmp_gt_f32_e32 vcc, s73, v0
	v_mul_f32_e32 v142, 0x4b800000, v0
	s_nop 0
	v_cndmask_b32_e32 v0, v0, v142, vcc
	v_rsq_f32_e32 v0, v0
	s_nop 0
	v_mul_f32_e32 v142, 0x45800000, v0
	v_cndmask_b32_e32 v0, v0, v142, vcc
	v_pk_mul_f32 v[154:155], v[60:61], v[0:1] op_sel_hi:[1,0]
	v_pk_mul_f32 v[152:153], v[58:59], v[0:1] op_sel_hi:[1,0]
	v_pk_mul_f32 v[156:157], v[52:53], v[0:1] op_sel_hi:[1,0]
	v_pk_mul_f32 v[158:159], v[50:51], v[0:1] op_sel_hi:[1,0]
	v_cvt_pk_bf16_f32 v152, v152, v153
	v_cvt_pk_bf16_f32 v153, v154, v155
	v_lshl_add_u64 v[142:143], v[140:141], 0, s[20:21]
	v_cvt_pk_bf16_f32 v154, v158, v159
	v_cvt_pk_bf16_f32 v155, v156, v157
	v_add_co_u32_e32 v156, vcc, s1, v140
	v_pk_mul_f32 v[158:159], v[54:55], v[0:1] op_sel_hi:[1,0]
	s_nop 0
	v_addc_co_u32_e32 v157, vcc, 0, v141, vcc
	flat_store_dwordx4 v[156:157], v[152:155]
	v_pk_mul_f32 v[156:157], v[56:57], v[0:1] op_sel_hi:[1,0]
	s_mov_b32 s1, 0x90000
	v_pk_mul_f32 v[154:155], v[64:65], v[0:1] op_sel_hi:[1,0]
	v_pk_mul_f32 v[152:153], v[62:63], v[0:1] op_sel_hi:[1,0]
	s_mov_b64 s[20:21], 0x90000
	v_cvt_pk_bf16_f32 v152, v152, v153
	v_cvt_pk_bf16_f32 v153, v154, v155
	v_cvt_pk_bf16_f32 v154, v158, v159
	v_cvt_pk_bf16_f32 v155, v156, v157
	flat_store_dwordx4 v[142:143], v[152:155] offset:256
	s_nop 1
	v_mov_b64_e32 v[142:143], v[172:173]
	v_xor_b32_e32 v0, v142, v143
	v_ashrrev_i32_e32 v0, 31, v0
	v_ffbh_i32_e32 v145, v143
	v_add_u32_e32 v0, 32, v0
	v_add_u32_e32 v145, -1, v145
	v_min_u32_e32 v0, v145, v0
	v_lshlrev_b64 v[142:143], v0, v[142:143]
	v_min_u32_e32 v142, 1, v142
	v_or_b32_e32 v142, v143, v142
	v_cvt_f32_i32_e32 v142, v142
	v_sub_u32_e32 v0, 32, v0
	v_ldexp_f32 v0, v142, v0
	v_mul_f32_e32 v0, 0x35800000, v0
	v_fmamk_f32 v0, v0, 0x3b000000, v180
	v_cmp_gt_f32_e32 vcc, s73, v0
	v_mul_f32_e32 v142, 0x4b800000, v0
	s_nop 0
	v_cndmask_b32_e32 v0, v0, v142, vcc
	v_rsq_f32_e32 v0, v0
	s_nop 0
	v_mul_f32_e32 v142, 0x45800000, v0
	v_cndmask_b32_e32 v0, v0, v142, vcc
	v_pk_mul_f32 v[154:155], v[44:45], v[0:1] op_sel_hi:[1,0]
	v_pk_mul_f32 v[152:153], v[42:43], v[0:1] op_sel_hi:[1,0]
	v_pk_mul_f32 v[156:157], v[36:37], v[0:1] op_sel_hi:[1,0]
	v_pk_mul_f32 v[158:159], v[34:35], v[0:1] op_sel_hi:[1,0]
	v_cvt_pk_bf16_f32 v152, v152, v153
	v_cvt_pk_bf16_f32 v153, v154, v155
	v_lshl_add_u64 v[142:143], v[140:141], 0, s[20:21]
	v_cvt_pk_bf16_f32 v154, v158, v159
	v_cvt_pk_bf16_f32 v155, v156, v157
	v_add_co_u32_e32 v156, vcc, s1, v140
	v_pk_mul_f32 v[158:159], v[38:39], v[0:1] op_sel_hi:[1,0]
	s_nop 0
	v_addc_co_u32_e32 v157, vcc, 0, v141, vcc
	flat_store_dwordx4 v[156:157], v[152:155]
	v_pk_mul_f32 v[156:157], v[40:41], v[0:1] op_sel_hi:[1,0]
	s_mov_b32 s1, 0xa0000
	v_pk_mul_f32 v[154:155], v[48:49], v[0:1] op_sel_hi:[1,0]
	v_pk_mul_f32 v[152:153], v[46:47], v[0:1] op_sel_hi:[1,0]
	s_mov_b64 s[20:21], 0xa0000
	v_cvt_pk_bf16_f32 v152, v152, v153
	v_cvt_pk_bf16_f32 v153, v154, v155
	v_cvt_pk_bf16_f32 v154, v158, v159
	v_cvt_pk_bf16_f32 v155, v156, v157
	flat_store_dwordx4 v[142:143], v[152:155] offset:256
	s_nop 1
	v_mov_b64_e32 v[142:143], v[174:175]
	v_xor_b32_e32 v0, v142, v143
	v_ashrrev_i32_e32 v0, 31, v0
	v_ffbh_i32_e32 v145, v143
	v_add_u32_e32 v0, 32, v0
	v_add_u32_e32 v145, -1, v145
	v_min_u32_e32 v0, v145, v0
	v_lshlrev_b64 v[142:143], v0, v[142:143]
	v_min_u32_e32 v142, 1, v142
	v_or_b32_e32 v142, v143, v142
	v_cvt_f32_i32_e32 v142, v142
	v_sub_u32_e32 v0, 32, v0
	v_ldexp_f32 v0, v142, v0
	v_mul_f32_e32 v0, 0x35800000, v0
	v_fmamk_f32 v0, v0, 0x3b000000, v180
	v_cmp_gt_f32_e32 vcc, s73, v0
	v_mul_f32_e32 v142, 0x4b800000, v0
	s_nop 0
	v_cndmask_b32_e32 v0, v0, v142, vcc
	v_rsq_f32_e32 v0, v0
	s_nop 0
	v_mul_f32_e32 v142, 0x45800000, v0
	v_cndmask_b32_e32 v0, v0, v142, vcc
	v_pk_mul_f32 v[154:155], v[28:29], v[0:1] op_sel_hi:[1,0]
	v_pk_mul_f32 v[152:153], v[26:27], v[0:1] op_sel_hi:[1,0]
	v_pk_mul_f32 v[156:157], v[20:21], v[0:1] op_sel_hi:[1,0]
	v_pk_mul_f32 v[158:159], v[18:19], v[0:1] op_sel_hi:[1,0]
	v_cvt_pk_bf16_f32 v152, v152, v153
	v_cvt_pk_bf16_f32 v153, v154, v155
	v_lshl_add_u64 v[142:143], v[140:141], 0, s[20:21]
	v_cvt_pk_bf16_f32 v154, v158, v159
	v_cvt_pk_bf16_f32 v155, v156, v157
	v_add_co_u32_e32 v156, vcc, s1, v140
	v_pk_mul_f32 v[158:159], v[22:23], v[0:1] op_sel_hi:[1,0]
	s_nop 0
	v_addc_co_u32_e32 v157, vcc, 0, v141, vcc
	flat_store_dwordx4 v[156:157], v[152:155]
	v_pk_mul_f32 v[156:157], v[24:25], v[0:1] op_sel_hi:[1,0]
	s_mov_b64 s[20:21], 0xb0000
	v_pk_mul_f32 v[154:155], v[32:33], v[0:1] op_sel_hi:[1,0]
	v_pk_mul_f32 v[152:153], v[30:31], v[0:1] op_sel_hi:[1,0]
	s_mov_b32 s1, 0xb0000
	v_cvt_pk_bf16_f32 v152, v152, v153
	v_cvt_pk_bf16_f32 v153, v154, v155
	v_cvt_pk_bf16_f32 v154, v158, v159
	v_cvt_pk_bf16_f32 v155, v156, v157
	flat_store_dwordx4 v[142:143], v[152:155] offset:256
	s_nop 1
	v_mov_b64_e32 v[132:133], v[176:177]
	v_xor_b32_e32 v0, v132, v133
	v_ashrrev_i32_e32 v0, 31, v0
	v_ffbh_i32_e32 v142, v133
	v_add_u32_e32 v0, 32, v0
	v_add_u32_e32 v142, -1, v142
	v_min_u32_e32 v0, v142, v0
	v_lshlrev_b64 v[132:133], v0, v[132:133]
	v_min_u32_e32 v132, 1, v132
	v_or_b32_e32 v132, v133, v132
	v_cvt_f32_i32_e32 v132, v132
	v_sub_u32_e32 v0, 32, v0
	v_ldexp_f32 v0, v132, v0
	v_mul_f32_e32 v0, 0x35800000, v0
	v_fmamk_f32 v0, v0, 0x3b000000, v180
	v_cmp_gt_f32_e32 vcc, s73, v0
	v_mul_f32_e32 v132, 0x4b800000, v0
	s_nop 0
	v_cndmask_b32_e32 v0, v0, v132, vcc
	v_rsq_f32_e32 v0, v0
	s_nop 0
	v_mul_f32_e32 v132, 0x45800000, v0
	v_cndmask_b32_e32 v0, v0, v132, vcc
	v_lshl_add_u64 v[132:133], v[140:141], 0, s[20:21]
	v_add_co_u32_e32 v140, vcc, s1, v140
	v_pk_mul_f32 v[142:143], v[12:13], v[0:1] op_sel_hi:[1,0]
	v_pk_mul_f32 v[152:153], v[10:11], v[0:1] op_sel_hi:[1,0]
	v_pk_mul_f32 v[154:155], v[2:3], v[0:1] op_sel_hi:[1,0]
	v_addc_co_u32_e32 v141, vcc, 0, v141, vcc
	v_pk_mul_f32 v[156:157], v[4:5], v[0:1] op_sel_hi:[1,0]
	v_cvt_pk_bf16_f32 v152, v152, v153
	v_cvt_pk_bf16_f32 v153, v142, v143
	v_cvt_pk_bf16_f32 v154, v154, v155
	v_pk_mul_f32 v[142:143], v[16:17], v[0:1] op_sel_hi:[1,0]
	v_cvt_pk_bf16_f32 v155, v156, v157
	flat_store_dwordx4 v[140:141], v[152:155]
	v_pk_mul_f32 v[140:141], v[14:15], v[0:1] op_sel_hi:[1,0]
	s_nop 0
	v_pk_mul_f32 v[152:153], v[8:9], v[0:1] op_sel_hi:[1,0]
	v_pk_mul_f32 v[154:155], v[6:7], v[0:1] op_sel_hi:[1,0]
	v_cvt_pk_bf16_f32 v140, v140, v141
	v_cvt_pk_bf16_f32 v141, v142, v143
	s_nop 0
	v_cvt_pk_bf16_f32 v142, v154, v155
	v_cvt_pk_bf16_f32 v143, v152, v153
	flat_store_dwordx4 v[132:133], v[140:143] offset:256
	s_cbranch_execz .LBB0_555

.LBB0_555:
	v_lshl_add_u64 v[132:133], v[130:131], 3, s[22:23]
	global_load_dwordx2 v[140:141], v[132:133], off
	global_load_dwordx2 v[164:165], v[132:133], off offset:128
	global_load_dwordx2 v[166:167], v[132:133], off offset:256
	global_load_dwordx2 v[168:169], v[132:133], off offset:384
	global_load_dwordx2 v[170:171], v[132:133], off offset:1024
	global_load_dwordx2 v[172:173], v[132:133], off offset:1152
	global_load_dwordx2 v[174:175], v[132:133], off offset:1280
	global_load_dwordx2 v[176:177], v[132:133], off offset:1408
	v_lshlrev_b64 v[178:179], 8, v[130:131]
	v_lshl_add_u64 v[178:179], s[10:11], 0, v[178:179]
	v_lshlrev_b32_e32 v240, 6, v144
	v_mov_b32_e32 v241, 0
	v_lshl_add_u64 v[178:179], v[178:179], 0, v[240:241]
	s_mov_b64 s[100:101], 0x1000
	global_load_dwordx4 v[182:185], v[178:179], off
	global_load_dwordx4 v[186:189], v[178:179], off offset:16
	global_load_dwordx4 v[190:193], v[178:179], off offset:32
	global_load_dwordx4 v[194:197], v[178:179], off offset:48
	v_lshl_add_u64 v[178:179], v[178:179], 0, s[100:101]
	global_load_dwordx4 v[198:201], v[178:179], off
	global_load_dwordx4 v[202:205], v[178:179], off offset:16
	global_load_dwordx4 v[206:209], v[178:179], off offset:32
	global_load_dwordx4 v[210:213], v[178:179], off offset:48
	v_lshl_add_u64 v[178:179], v[178:179], 0, s[100:101]
	global_load_dwordx4 v[214:217], v[178:179], off
	global_load_dwordx4 v[218:221], v[178:179], off offset:16
	global_load_dwordx4 v[222:225], v[178:179], off offset:32
	global_load_dwordx4 v[226:229], v[178:179], off offset:48
	s_lshl_b32 s0, s0, 8
	v_readlane_b32 s1, v254, 57
	s_add_i32 s94, s1, s0
	s_lshl_b64 s[0:1], s[94:95], 1
	s_add_u32 s20, s58, s0
	s_addc_u32 s21, s59, s1
	s_waitcnt vmcnt(0)
	v_xor_b32_e32 v0, v140, v141
	v_ashrrev_i32_e32 v0, 31, v0
	v_ffbh_i32_e32 v142, v141
	v_add_u32_e32 v0, 32, v0
	v_add_u32_e32 v142, -1, v142
	v_min_u32_e32 v0, v142, v0
	v_lshlrev_b64 v[140:141], v0, v[140:141]
	v_min_u32_e32 v140, 1, v140
	v_or_b32_e32 v140, v141, v140
	v_cvt_f32_i32_e32 v140, v140
	v_sub_u32_e32 v0, 32, v0
	v_lshlrev_b64 v[142:143], 8, v[130:131]
	v_lshl_add_u64 v[142:143], s[10:11], 0, v[142:143]
	v_ldexp_f32 v0, v140, v0
	v_mul_f32_e32 v0, 0x35800000, v0
	v_fmamk_f32 v0, v0, 0x3b000000, v180
	v_cmp_gt_f32_e32 vcc, s73, v0
	v_mul_f32_e32 v140, 0x4b800000, v0
	s_nop 0
	v_cndmask_b32_e32 v0, v0, v140, vcc
	v_rsq_f32_e32 v0, v0
	s_nop 0
	v_mul_f32_e32 v140, 0x45800000, v0
	v_cndmask_b32_e32 v140, v0, v140, vcc
	v_lshlrev_b32_e32 v0, 6, v144
	v_lshl_add_u64 v[160:161], v[142:143], 0, v[0:1]
	v_mov_b64_e32 v[152:153], v[182:183]
	v_mov_b64_e32 v[154:155], v[184:185]
	v_mov_b32_e32 v142, v122
	v_mov_b32_e32 v143, v126
	v_pk_mul_f32 v[142:143], v[142:143], v[140:141] op_sel_hi:[1,0]
	v_mov_b32_e32 v126, v123
	v_pk_mul_f32 v[156:157], v[152:153], v[142:143]
	s_nop 0
	v_sub_f32_e32 v141, v156, v157
	v_mov_b64_e32 v[156:157], v[190:191]
	v_mov_b64_e32 v[158:159], v[192:193]
	v_pk_mul_f32 v[142:143], v[152:153], v[142:143] op_sel:[0,1] op_sel_hi:[1,0]
	s_nop 0
	v_add_f32_e32 v122, v142, v143
	v_mov_b32_e32 v142, v114
	v_mov_b32_e32 v143, v118
	v_pk_mul_f32 v[152:153], v[142:143], v[140:141] op_sel_hi:[1,0]
	v_mov_b32_e32 v118, v115
	v_pk_mul_f32 v[114:115], v[118:119], v[140:141] op_sel_hi:[1,0]
	v_pk_mul_f32 v[142:143], v[156:157], v[152:153]
	v_pk_mul_f32 v[152:153], v[156:157], v[152:153] op_sel:[0,1] op_sel_hi:[1,0]
	v_sub_f32_e32 v143, v142, v143
	v_add_f32_e32 v142, v152, v153
	v_pk_mul_f32 v[152:153], v[126:127], v[140:141] op_sel_hi:[1,0]
	v_pk_mul_f32 v[118:119], v[158:159], v[114:115]
	v_pk_mul_f32 v[126:127], v[154:155], v[152:153]
	v_pk_mul_f32 v[152:153], v[154:155], v[152:153] op_sel:[0,1] op_sel_hi:[1,0]
	v_pk_mul_f32 v[114:115], v[158:159], v[114:115] op_sel:[0,1] op_sel_hi:[1,0]
	v_add_f32_e32 v123, v152, v153
	v_mov_b64_e32 v[152:153], v[186:187]
	v_mov_b64_e32 v[154:155], v[188:189]
	v_sub_f32_e32 v119, v118, v119
	v_add_f32_e32 v118, v114, v115
	v_mov_b32_e32 v114, v124
	v_mov_b32_e32 v115, v128
	v_pk_mul_f32 v[114:115], v[114:115], v[140:141] op_sel_hi:[1,0]
	v_sub_f32_e32 v126, v126, v127
	v_mov_b32_e32 v128, v125
	v_pk_mul_f32 v[156:157], v[152:153], v[114:115]
	s_nop 0
	v_sub_f32_e32 v127, v156, v157
	v_mov_b64_e32 v[156:157], v[194:195]
	v_mov_b64_e32 v[158:159], v[196:197]
	v_lshl_add_u64 v[178:179], v[178:179], 0, s[100:101]
	global_load_dwordx4 v[182:185], v[178:179], off
	global_load_dwordx4 v[186:189], v[178:179], off offset:16
	global_load_dwordx4 v[190:193], v[178:179], off offset:32
	global_load_dwordx4 v[194:197], v[178:179], off offset:48
	v_pk_mul_f32 v[114:115], v[114:115], v[152:153] op_sel:[1,0] op_sel_hi:[0,1]
	v_add_f32_e32 v145, v114, v115
	v_mov_b32_e32 v114, v116
	v_mov_b32_e32 v115, v120
	v_pk_mul_f32 v[114:115], v[114:115], v[140:141] op_sel_hi:[1,0]
	v_mov_b32_e32 v120, v117
	v_pk_mul_f32 v[152:153], v[114:115], v[156:157]
	v_pk_mul_f32 v[114:115], v[114:115], v[156:157] op_sel:[1,0] op_sel_hi:[0,1]
	v_sub_f32_e32 v152, v152, v153
	v_add_f32_e32 v153, v114, v115
	v_pk_mul_f32 v[114:115], v[128:129], v[140:141] op_sel_hi:[1,0]
	s_nop 0
	v_pk_mul_f32 v[124:125], v[114:115], v[154:155]
	v_pk_mul_f32 v[114:115], v[114:115], v[154:155] op_sel:[1,0] op_sel_hi:[0,1]
	v_add_f32_e32 v128, v114, v115
	v_pk_mul_f32 v[114:115], v[120:121], v[140:141] op_sel_hi:[1,0]
	v_sub_f32_e32 v125, v124, v125
	v_pk_mul_f32 v[116:117], v[114:115], v[158:159]
	v_pk_mul_f32 v[114:115], v[114:115], v[158:159] op_sel:[1,0] op_sel_hi:[0,1]
	v_add_f32_e32 v140, v114, v115
	v_lshlrev_b64 v[114:115], 11, v[130:131]
	v_sub_f32_e32 v129, v116, v117
	v_lshl_add_u64 v[116:117], s[20:21], 0, v[114:115]
	v_lshlrev_b32_e32 v114, 4, v144
	v_mov_b32_e32 v115, v1
	v_lshl_add_u64 v[120:121], v[116:117], 0, v[114:115]
	v_cvt_pk_bf16_f32 v124, v141, v126
	v_cvt_pk_bf16_f32 v125, v127, v125
	v_cvt_pk_bf16_f32 v126, v143, v119
	v_cvt_pk_bf16_f32 v127, v152, v129
	flat_store_dwordx4 v[120:121], v[124:127]
	v_cvt_pk_bf16_f32 v116, v122, v123
	v_cvt_pk_bf16_f32 v117, v145, v128
	v_cvt_pk_bf16_f32 v118, v142, v118
	v_cvt_pk_bf16_f32 v119, v153, v140
	flat_store_dwordx4 v[120:121], v[116:119] offset:64
	s_nop 1
	v_mov_b64_e32 v[116:117], v[164:165]
	v_mov_b32_e32 v122, v106
	v_mov_b32_e32 v123, v110
	v_mov_b32_e32 v110, v107
	v_xor_b32_e32 v118, v116, v117
	v_ashrrev_i32_e32 v118, 31, v118
	v_ffbh_i32_e32 v119, v117
	v_add_u32_e32 v118, 32, v118
	v_add_u32_e32 v119, -1, v119
	v_min_u32_e32 v118, v119, v118
	v_lshlrev_b64 v[116:117], v118, v[116:117]
	v_min_u32_e32 v116, 1, v116
	v_or_b32_e32 v116, v117, v116
	v_sub_u32_e32 v117, 32, v118
	v_lshlrev_b64 v[118:119], 8, v[138:139]
	v_lshl_add_u64 v[118:119], s[10:11], 0, v[118:119]
	v_lshl_add_u64 v[126:127], v[118:119], 0, v[0:1]
	v_mov_b64_e32 v[118:119], v[198:199]
	v_mov_b64_e32 v[120:121], v[200:201]
	v_cvt_f32_i32_e32 v116, v116
	v_ldexp_f32 v116, v116, v117
	v_mul_f32_e32 v116, 0x35800000, v116
	v_fmamk_f32 v116, v116, 0x3b000000, v180
	v_cmp_gt_f32_e32 vcc, s73, v116
	v_mul_f32_e32 v117, 0x4b800000, v116
	s_nop 0
	v_cndmask_b32_e32 v116, v116, v117, vcc
	v_rsq_f32_e32 v116, v116
	s_nop 0
	v_mul_f32_e32 v117, 0x45800000, v116
	v_cndmask_b32_e32 v116, v116, v117, vcc
	v_pk_mul_f32 v[122:123], v[122:123], v[116:117] op_sel_hi:[1,0]
	v_pk_mul_f32 v[124:125], v[118:119], v[122:123]
	s_nop 0
	v_sub_f32_e32 v117, v124, v125
	v_pk_mul_f32 v[118:119], v[118:119], v[122:123] op_sel:[0,1] op_sel_hi:[1,0]
	v_mov_b64_e32 v[122:123], v[206:207]
	v_mov_b64_e32 v[124:125], v[208:209]
	v_add_f32_e32 v106, v118, v119
	v_mov_b32_e32 v118, v98
	v_mov_b32_e32 v119, v102
	v_pk_mul_f32 v[128:129], v[118:119], v[116:117] op_sel_hi:[1,0]
	v_pk_mul_f32 v[110:111], v[110:111], v[116:117] op_sel_hi:[1,0]
	v_mov_b32_e32 v102, v99
	v_pk_mul_f32 v[102:103], v[102:103], v[116:117] op_sel_hi:[1,0]
	v_pk_mul_f32 v[118:119], v[122:123], v[128:129]
	v_pk_mul_f32 v[122:123], v[122:123], v[128:129] op_sel:[0,1] op_sel_hi:[1,0]
	v_sub_f32_e32 v118, v118, v119
	v_add_f32_e32 v98, v122, v123
	v_pk_mul_f32 v[122:123], v[120:121], v[110:111]
	v_pk_mul_f32 v[110:111], v[120:121], v[110:111] op_sel:[0,1] op_sel_hi:[1,0]
	v_sub_f32_e32 v107, v122, v123
	v_mov_b64_e32 v[120:121], v[202:203]
	v_mov_b64_e32 v[122:123], v[204:205]
	v_add_f32_e32 v119, v110, v111
	v_pk_mul_f32 v[110:111], v[124:125], v[102:103]
	v_pk_mul_f32 v[102:103], v[124:125], v[102:103] op_sel:[0,1] op_sel_hi:[1,0]
	v_mov_b64_e32 v[124:125], v[210:211]
	v_mov_b64_e32 v[126:127], v[212:213]
	s_mov_b32 s100, 0x5000
	v_lshl_add_u64 v[178:179], v[178:179], 0, s[100:101]
	s_mov_b32 s100, 0x1000
	global_load_dwordx4 v[198:201], v[178:179], off
	global_load_dwordx4 v[202:205], v[178:179], off offset:16
	global_load_dwordx4 v[206:209], v[178:179], off offset:32
	global_load_dwordx4 v[210:213], v[178:179], off offset:48
	v_add_f32_e32 v128, v102, v103
	v_mov_b32_e32 v102, v108
	v_mov_b32_e32 v103, v112
	v_pk_mul_f32 v[102:103], v[102:103], v[116:117] op_sel_hi:[1,0]
	v_sub_f32_e32 v99, v110, v111
	v_mov_b32_e32 v112, v109
	v_pk_mul_f32 v[110:111], v[120:121], v[102:103]
	v_pk_mul_f32 v[102:103], v[102:103], v[120:121] op_sel:[1,0] op_sel_hi:[0,1]
	v_add_f32_e32 v120, v102, v103
	v_mov_b32_e32 v102, v100
	v_mov_b32_e32 v103, v104
	v_pk_mul_f32 v[102:103], v[102:103], v[116:117] op_sel_hi:[1,0]
	v_sub_f32_e32 v129, v110, v111
	v_pk_mul_f32 v[110:111], v[102:103], v[124:125]
	v_pk_mul_f32 v[102:103], v[102:103], v[124:125] op_sel:[1,0] op_sel_hi:[0,1]
	v_sub_f32_e32 v110, v110, v111
	v_add_f32_e32 v111, v102, v103
	v_pk_mul_f32 v[102:103], v[112:113], v[116:117] op_sel_hi:[1,0]
	v_mov_b32_e32 v104, v101
	v_pk_mul_f32 v[108:109], v[102:103], v[122:123]
	v_pk_mul_f32 v[102:103], v[102:103], v[122:123] op_sel:[1,0] op_sel_hi:[0,1]
	v_pk_mul_f32 v[100:101], v[104:105], v[116:117] op_sel_hi:[1,0]
	v_sub_f32_e32 v108, v108, v109
	v_add_f32_e32 v109, v102, v103
	v_pk_mul_f32 v[102:103], v[100:101], v[126:127]
	v_pk_mul_f32 v[100:101], v[100:101], v[126:127] op_sel:[1,0] op_sel_hi:[0,1]
	v_add_f32_e32 v112, v100, v101
	v_lshlrev_b64 v[100:101], 11, v[138:139]
	v_sub_f32_e32 v103, v102, v103
	v_lshl_add_u64 v[100:101], s[20:21], 0, v[100:101]
	v_lshl_add_u64 v[104:105], v[100:101], 0, v[114:115]
	v_cvt_pk_bf16_f32 v100, v117, v107
	v_cvt_pk_bf16_f32 v101, v129, v108
	v_cvt_pk_bf16_f32 v102, v118, v99
	v_cvt_pk_bf16_f32 v103, v110, v103
	flat_store_dwordx4 v[104:105], v[100:103]
	s_nop 1
	v_cvt_pk_bf16_f32 v100, v106, v119
	v_cvt_pk_bf16_f32 v101, v120, v109
	v_cvt_pk_bf16_f32 v102, v98, v128
	v_cvt_pk_bf16_f32 v103, v111, v112
	flat_store_dwordx4 v[104:105], v[100:103] offset:64
	s_nop 1
	v_mov_b64_e32 v[98:99], v[166:167]
	v_mov_b32_e32 v104, v90
	v_mov_b32_e32 v105, v94
	v_mov_b32_e32 v94, v91
	v_xor_b32_e32 v100, v98, v99
	v_ashrrev_i32_e32 v100, 31, v100
	v_ffbh_i32_e32 v101, v99
	v_add_u32_e32 v100, 32, v100
	v_add_u32_e32 v101, -1, v101
	v_min_u32_e32 v100, v101, v100
	v_lshlrev_b64 v[98:99], v100, v[98:99]
	v_min_u32_e32 v98, 1, v98
	v_or_b32_e32 v98, v99, v98
	v_sub_u32_e32 v99, 32, v100
	v_lshlrev_b64 v[100:101], 8, v[136:137]
	v_lshl_add_u64 v[100:101], s[10:11], 0, v[100:101]
	v_lshl_add_u64 v[108:109], v[100:101], 0, v[0:1]
	v_mov_b64_e32 v[100:101], v[214:215]
	v_mov_b64_e32 v[102:103], v[216:217]
	v_cvt_f32_i32_e32 v98, v98
	v_ldexp_f32 v98, v98, v99
	v_mul_f32_e32 v98, 0x35800000, v98
	v_fmamk_f32 v98, v98, 0x3b000000, v180
	v_cmp_gt_f32_e32 vcc, s73, v98
	v_mul_f32_e32 v99, 0x4b800000, v98
	s_nop 0
	v_cndmask_b32_e32 v98, v98, v99, vcc
	v_rsq_f32_e32 v98, v98
	s_nop 0
	v_mul_f32_e32 v99, 0x45800000, v98
	v_cndmask_b32_e32 v98, v98, v99, vcc
	v_pk_mul_f32 v[104:105], v[104:105], v[98:99] op_sel_hi:[1,0]
	v_pk_mul_f32 v[106:107], v[100:101], v[104:105]
	s_nop 0
	v_sub_f32_e32 v99, v106, v107
	v_pk_mul_f32 v[100:101], v[100:101], v[104:105] op_sel:[0,1] op_sel_hi:[1,0]
	v_mov_b64_e32 v[104:105], v[222:223]
	v_mov_b64_e32 v[106:107], v[224:225]
	v_add_f32_e32 v90, v100, v101
	v_mov_b32_e32 v100, v82
	v_mov_b32_e32 v101, v86
	v_pk_mul_f32 v[110:111], v[100:101], v[98:99] op_sel_hi:[1,0]
	v_pk_mul_f32 v[94:95], v[94:95], v[98:99] op_sel_hi:[1,0]
	v_mov_b32_e32 v86, v83
	v_pk_mul_f32 v[86:87], v[86:87], v[98:99] op_sel_hi:[1,0]
	v_pk_mul_f32 v[100:101], v[104:105], v[110:111]
	v_pk_mul_f32 v[104:105], v[104:105], v[110:111] op_sel:[0,1] op_sel_hi:[1,0]
	v_sub_f32_e32 v100, v100, v101
	v_add_f32_e32 v82, v104, v105
	v_pk_mul_f32 v[104:105], v[102:103], v[94:95]
	v_pk_mul_f32 v[94:95], v[102:103], v[94:95] op_sel:[0,1] op_sel_hi:[1,0]
	v_sub_f32_e32 v91, v104, v105
	v_mov_b64_e32 v[102:103], v[218:219]
	v_mov_b64_e32 v[104:105], v[220:221]
	v_add_f32_e32 v101, v94, v95
	v_pk_mul_f32 v[94:95], v[106:107], v[86:87]
	v_pk_mul_f32 v[86:87], v[106:107], v[86:87] op_sel:[0,1] op_sel_hi:[1,0]
	v_mov_b64_e32 v[106:107], v[226:227]
	v_mov_b64_e32 v[108:109], v[228:229]
	v_lshl_add_u64 v[178:179], v[178:179], 0, s[100:101]
	global_load_dwordx4 v[214:217], v[178:179], off
	global_load_dwordx4 v[218:221], v[178:179], off offset:16
	global_load_dwordx4 v[222:225], v[178:179], off offset:32
	global_load_dwordx4 v[226:229], v[178:179], off offset:48
	v_add_f32_e32 v110, v86, v87
	v_mov_b32_e32 v86, v92
	v_mov_b32_e32 v87, v96
	v_pk_mul_f32 v[86:87], v[86:87], v[98:99] op_sel_hi:[1,0]
	v_sub_f32_e32 v83, v94, v95
	v_mov_b32_e32 v96, v93
	v_pk_mul_f32 v[94:95], v[102:103], v[86:87]
	v_pk_mul_f32 v[86:87], v[86:87], v[102:103] op_sel:[1,0] op_sel_hi:[0,1]
	v_add_f32_e32 v102, v86, v87
	v_mov_b32_e32 v86, v84
	v_mov_b32_e32 v87, v88
	v_pk_mul_f32 v[86:87], v[86:87], v[98:99] op_sel_hi:[1,0]
	v_sub_f32_e32 v111, v94, v95
	v_pk_mul_f32 v[94:95], v[86:87], v[106:107]
	v_pk_mul_f32 v[86:87], v[86:87], v[106:107] op_sel:[1,0] op_sel_hi:[0,1]
	v_sub_f32_e32 v94, v94, v95
	v_add_f32_e32 v95, v86, v87
	v_pk_mul_f32 v[86:87], v[96:97], v[98:99] op_sel_hi:[1,0]
	v_mov_b32_e32 v88, v85
	v_pk_mul_f32 v[92:93], v[86:87], v[104:105]
	v_pk_mul_f32 v[86:87], v[86:87], v[104:105] op_sel:[1,0] op_sel_hi:[0,1]
	v_pk_mul_f32 v[84:85], v[88:89], v[98:99] op_sel_hi:[1,0]
	v_sub_f32_e32 v92, v92, v93
	v_add_f32_e32 v93, v86, v87
	v_pk_mul_f32 v[86:87], v[84:85], v[108:109]
	v_pk_mul_f32 v[84:85], v[84:85], v[108:109] op_sel:[1,0] op_sel_hi:[0,1]
	v_add_f32_e32 v96, v84, v85
	v_lshlrev_b64 v[84:85], 11, v[136:137]
	v_sub_f32_e32 v87, v86, v87
	v_lshl_add_u64 v[84:85], s[20:21], 0, v[84:85]
	v_lshl_add_u64 v[88:89], v[84:85], 0, v[114:115]
	v_cvt_pk_bf16_f32 v84, v99, v91
	v_cvt_pk_bf16_f32 v85, v111, v92
	v_cvt_pk_bf16_f32 v86, v100, v83
	v_cvt_pk_bf16_f32 v87, v94, v87
	flat_store_dwordx4 v[88:89], v[84:87]
	s_nop 1
	v_cvt_pk_bf16_f32 v84, v90, v101
	v_cvt_pk_bf16_f32 v85, v102, v93
	v_cvt_pk_bf16_f32 v86, v82, v110
	v_cvt_pk_bf16_f32 v87, v95, v96
	flat_store_dwordx4 v[88:89], v[84:87] offset:64
	s_nop 1
	v_mov_b64_e32 v[82:83], v[168:169]
	v_mov_b32_e32 v88, v74
	v_mov_b32_e32 v89, v78
	v_mov_b32_e32 v78, v75
	s_waitcnt vmcnt(14)
	v_xor_b32_e32 v84, v82, v83
	v_ashrrev_i32_e32 v84, 31, v84
	v_ffbh_i32_e32 v85, v83
	v_add_u32_e32 v84, 32, v84
	v_add_u32_e32 v85, -1, v85
	v_min_u32_e32 v84, v85, v84
	v_lshlrev_b64 v[82:83], v84, v[82:83]
	v_min_u32_e32 v82, 1, v82
	v_or_b32_e32 v82, v83, v82
	v_sub_u32_e32 v83, 32, v84
	v_lshlrev_b64 v[84:85], 8, v[134:135]
	v_lshl_add_u64 v[84:85], s[10:11], 0, v[84:85]
	v_lshl_add_u64 v[92:93], v[84:85], 0, v[0:1]
	v_mov_b64_e32 v[84:85], v[182:183]
	v_mov_b64_e32 v[86:87], v[184:185]
	v_cvt_f32_i32_e32 v82, v82
	v_ldexp_f32 v82, v82, v83
	v_mul_f32_e32 v82, 0x35800000, v82
	v_fmamk_f32 v82, v82, 0x3b000000, v180
	v_cmp_gt_f32_e32 vcc, s73, v82
	v_mul_f32_e32 v83, 0x4b800000, v82
	s_nop 0
	v_cndmask_b32_e32 v82, v82, v83, vcc
	v_rsq_f32_e32 v82, v82
	s_nop 0
	v_mul_f32_e32 v83, 0x45800000, v82
	v_cndmask_b32_e32 v82, v82, v83, vcc
	v_pk_mul_f32 v[88:89], v[88:89], v[82:83] op_sel_hi:[1,0]
	v_pk_mul_f32 v[90:91], v[84:85], v[88:89]
	s_nop 0
	v_sub_f32_e32 v83, v90, v91
	v_pk_mul_f32 v[84:85], v[84:85], v[88:89] op_sel:[0,1] op_sel_hi:[1,0]
	v_mov_b64_e32 v[88:89], v[190:191]
	v_mov_b64_e32 v[90:91], v[192:193]
	v_add_f32_e32 v74, v84, v85
	v_mov_b32_e32 v84, v66
	v_mov_b32_e32 v85, v70
	v_pk_mul_f32 v[94:95], v[84:85], v[82:83] op_sel_hi:[1,0]
	v_pk_mul_f32 v[78:79], v[78:79], v[82:83] op_sel_hi:[1,0]
	v_mov_b32_e32 v70, v67
	v_pk_mul_f32 v[70:71], v[70:71], v[82:83] op_sel_hi:[1,0]
	v_pk_mul_f32 v[84:85], v[88:89], v[94:95]
	v_pk_mul_f32 v[88:89], v[88:89], v[94:95] op_sel:[0,1] op_sel_hi:[1,0]
	v_sub_f32_e32 v84, v84, v85
	v_add_f32_e32 v66, v88, v89
	v_pk_mul_f32 v[88:89], v[86:87], v[78:79]
	v_pk_mul_f32 v[78:79], v[86:87], v[78:79] op_sel:[0,1] op_sel_hi:[1,0]
	v_sub_f32_e32 v75, v88, v89
	v_mov_b64_e32 v[86:87], v[186:187]
	v_mov_b64_e32 v[88:89], v[188:189]
	v_add_f32_e32 v85, v78, v79
	v_pk_mul_f32 v[78:79], v[90:91], v[70:71]
	v_pk_mul_f32 v[70:71], v[90:91], v[70:71] op_sel:[0,1] op_sel_hi:[1,0]
	v_mov_b64_e32 v[90:91], v[194:195]
	v_mov_b64_e32 v[92:93], v[196:197]
	v_lshl_add_u64 v[178:179], v[178:179], 0, s[100:101]
	global_load_dwordx4 v[182:185], v[178:179], off
	global_load_dwordx4 v[186:189], v[178:179], off offset:16
	global_load_dwordx4 v[190:193], v[178:179], off offset:32
	global_load_dwordx4 v[194:197], v[178:179], off offset:48
	v_add_f32_e32 v94, v70, v71
	v_mov_b32_e32 v70, v76
	v_mov_b32_e32 v71, v80
	v_pk_mul_f32 v[70:71], v[70:71], v[82:83] op_sel_hi:[1,0]
	v_sub_f32_e32 v67, v78, v79
	v_mov_b32_e32 v80, v77
	v_pk_mul_f32 v[78:79], v[86:87], v[70:71]
	v_pk_mul_f32 v[70:71], v[70:71], v[86:87] op_sel:[1,0] op_sel_hi:[0,1]
	v_add_f32_e32 v86, v70, v71
	v_mov_b32_e32 v70, v68
	v_mov_b32_e32 v71, v72
	v_pk_mul_f32 v[70:71], v[70:71], v[82:83] op_sel_hi:[1,0]
	v_sub_f32_e32 v95, v78, v79
	v_pk_mul_f32 v[78:79], v[70:71], v[90:91]
	v_pk_mul_f32 v[70:71], v[70:71], v[90:91] op_sel:[1,0] op_sel_hi:[0,1]
	v_sub_f32_e32 v78, v78, v79
	v_add_f32_e32 v79, v70, v71
	v_pk_mul_f32 v[70:71], v[80:81], v[82:83] op_sel_hi:[1,0]
	v_mov_b32_e32 v72, v69
	v_pk_mul_f32 v[76:77], v[70:71], v[88:89]
	v_pk_mul_f32 v[70:71], v[70:71], v[88:89] op_sel:[1,0] op_sel_hi:[0,1]
	v_pk_mul_f32 v[68:69], v[72:73], v[82:83] op_sel_hi:[1,0]
	v_sub_f32_e32 v76, v76, v77
	v_add_f32_e32 v77, v70, v71
	v_pk_mul_f32 v[70:71], v[68:69], v[92:93]
	v_pk_mul_f32 v[68:69], v[68:69], v[92:93] op_sel:[1,0] op_sel_hi:[0,1]
	v_add_f32_e32 v80, v68, v69
	v_lshlrev_b64 v[68:69], 11, v[134:135]
	v_sub_f32_e32 v71, v70, v71
	v_lshl_add_u64 v[68:69], s[20:21], 0, v[68:69]
	v_lshl_add_u64 v[72:73], v[68:69], 0, v[114:115]
	v_cvt_pk_bf16_f32 v68, v83, v75
	v_cvt_pk_bf16_f32 v69, v95, v76
	v_cvt_pk_bf16_f32 v70, v84, v67
	v_cvt_pk_bf16_f32 v71, v78, v71
	flat_store_dwordx4 v[72:73], v[68:71]
	v_mov_b32_e32 v75, v62
	v_mov_b32_e32 v62, v59
	v_cvt_pk_bf16_f32 v68, v74, v85
	v_cvt_pk_bf16_f32 v69, v86, v77
	v_cvt_pk_bf16_f32 v70, v66, v94
	v_cvt_pk_bf16_f32 v71, v79, v80
	flat_store_dwordx4 v[72:73], v[68:71] offset:64
	s_nop 1
	v_mov_b64_e32 v[68:69], v[170:171]
	v_add_u32_e32 v66, 0x80, v130
	v_ashrrev_i32_e32 v67, 31, v66
	v_mov_b32_e32 v74, v58
	s_waitcnt vmcnt(14)
	v_xor_b32_e32 v70, v68, v69
	v_ashrrev_i32_e32 v70, 31, v70
	v_ffbh_i32_e32 v71, v69
	v_add_u32_e32 v70, 32, v70
	v_add_u32_e32 v71, -1, v71
	v_min_u32_e32 v70, v71, v70
	v_lshlrev_b64 v[68:69], v70, v[68:69]
	v_min_u32_e32 v68, 1, v68
	v_or_b32_e32 v68, v69, v68
	v_sub_u32_e32 v69, 32, v70
	v_lshlrev_b64 v[70:71], 8, v[66:67]
	v_lshl_add_u64 v[70:71], s[10:11], 0, v[70:71]
	v_lshl_add_u64 v[78:79], v[70:71], 0, v[0:1]
	v_mov_b64_e32 v[70:71], v[198:199]
	v_mov_b64_e32 v[72:73], v[200:201]
	v_cvt_f32_i32_e32 v68, v68
	v_ldexp_f32 v68, v68, v69
	v_mul_f32_e32 v68, 0x35800000, v68
	v_fmamk_f32 v68, v68, 0x3b000000, v180
	v_cmp_gt_f32_e32 vcc, s73, v68
	v_mul_f32_e32 v69, 0x4b800000, v68
	s_nop 0
	v_cndmask_b32_e32 v68, v68, v69, vcc
	v_rsq_f32_e32 v68, v68
	s_nop 0
	v_mul_f32_e32 v69, 0x45800000, v68
	v_cndmask_b32_e32 v68, v68, v69, vcc
	v_pk_mul_f32 v[74:75], v[74:75], v[68:69] op_sel_hi:[1,0]
	v_pk_mul_f32 v[76:77], v[70:71], v[74:75]
	s_nop 0
	v_sub_f32_e32 v69, v76, v77
	v_pk_mul_f32 v[70:71], v[70:71], v[74:75] op_sel:[0,1] op_sel_hi:[1,0]
	v_mov_b64_e32 v[74:75], v[206:207]
	v_mov_b64_e32 v[76:77], v[208:209]
	v_add_f32_e32 v58, v70, v71
	v_mov_b32_e32 v70, v50
	v_mov_b32_e32 v71, v54
	v_pk_mul_f32 v[80:81], v[70:71], v[68:69] op_sel_hi:[1,0]
	v_pk_mul_f32 v[62:63], v[62:63], v[68:69] op_sel_hi:[1,0]
	v_mov_b32_e32 v54, v51
	v_pk_mul_f32 v[54:55], v[54:55], v[68:69] op_sel_hi:[1,0]
	v_pk_mul_f32 v[70:71], v[74:75], v[80:81]
	v_pk_mul_f32 v[74:75], v[74:75], v[80:81] op_sel:[0,1] op_sel_hi:[1,0]
	v_sub_f32_e32 v70, v70, v71
	v_add_f32_e32 v50, v74, v75
	v_pk_mul_f32 v[74:75], v[72:73], v[62:63]
	v_pk_mul_f32 v[62:63], v[72:73], v[62:63] op_sel:[0,1] op_sel_hi:[1,0]
	v_sub_f32_e32 v59, v74, v75
	v_mov_b64_e32 v[72:73], v[202:203]
	v_mov_b64_e32 v[74:75], v[204:205]
	v_add_f32_e32 v71, v62, v63
	v_pk_mul_f32 v[62:63], v[76:77], v[54:55]
	v_pk_mul_f32 v[54:55], v[76:77], v[54:55] op_sel:[0,1] op_sel_hi:[1,0]
	v_mov_b64_e32 v[76:77], v[210:211]
	v_mov_b64_e32 v[78:79], v[212:213]
	v_lshl_add_u64 v[178:179], v[178:179], 0, s[100:101]
	global_load_dwordx4 v[198:201], v[178:179], off
	global_load_dwordx4 v[202:205], v[178:179], off offset:16
	global_load_dwordx4 v[206:209], v[178:179], off offset:32
	global_load_dwordx4 v[210:213], v[178:179], off offset:48
	v_add_f32_e32 v80, v54, v55
	v_mov_b32_e32 v54, v60
	v_mov_b32_e32 v55, v64
	v_pk_mul_f32 v[54:55], v[54:55], v[68:69] op_sel_hi:[1,0]
	v_sub_f32_e32 v51, v62, v63
	v_mov_b32_e32 v64, v61
	v_pk_mul_f32 v[62:63], v[72:73], v[54:55]
	v_pk_mul_f32 v[54:55], v[54:55], v[72:73] op_sel:[1,0] op_sel_hi:[0,1]
	v_add_f32_e32 v72, v54, v55
	v_mov_b32_e32 v54, v52
	v_mov_b32_e32 v55, v56
	v_pk_mul_f32 v[54:55], v[54:55], v[68:69] op_sel_hi:[1,0]
	v_sub_f32_e32 v81, v62, v63
	v_pk_mul_f32 v[62:63], v[54:55], v[76:77]
	v_pk_mul_f32 v[54:55], v[54:55], v[76:77] op_sel:[1,0] op_sel_hi:[0,1]
	v_sub_f32_e32 v62, v62, v63
	v_add_f32_e32 v63, v54, v55
	v_pk_mul_f32 v[54:55], v[64:65], v[68:69] op_sel_hi:[1,0]
	v_mov_b32_e32 v56, v53
	v_pk_mul_f32 v[60:61], v[54:55], v[74:75]
	v_pk_mul_f32 v[54:55], v[54:55], v[74:75] op_sel:[1,0] op_sel_hi:[0,1]
	v_pk_mul_f32 v[52:53], v[56:57], v[68:69] op_sel_hi:[1,0]
	v_sub_f32_e32 v60, v60, v61
	v_add_f32_e32 v61, v54, v55
	v_pk_mul_f32 v[54:55], v[52:53], v[78:79]
	v_pk_mul_f32 v[52:53], v[52:53], v[78:79] op_sel:[1,0] op_sel_hi:[0,1]
	v_add_f32_e32 v64, v52, v53
	v_lshlrev_b64 v[52:53], 11, v[66:67]
	v_sub_f32_e32 v55, v54, v55
	v_lshl_add_u64 v[52:53], s[20:21], 0, v[52:53]
	v_lshl_add_u64 v[56:57], v[52:53], 0, v[114:115]
	v_cvt_pk_bf16_f32 v52, v69, v59
	v_cvt_pk_bf16_f32 v53, v81, v60
	v_cvt_pk_bf16_f32 v54, v70, v51
	v_cvt_pk_bf16_f32 v55, v62, v55
	flat_store_dwordx4 v[56:57], v[52:55]
	v_mov_b32_e32 v59, v46
	v_mov_b32_e32 v46, v43
	v_cvt_pk_bf16_f32 v52, v58, v71
	v_cvt_pk_bf16_f32 v53, v72, v61
	v_cvt_pk_bf16_f32 v54, v50, v80
	v_cvt_pk_bf16_f32 v55, v63, v64
	flat_store_dwordx4 v[56:57], v[52:55] offset:64
	s_nop 1
	v_mov_b64_e32 v[52:53], v[172:173]
	v_add_u32_e32 v50, 0x90, v130
	v_ashrrev_i32_e32 v51, 31, v50
	v_mov_b32_e32 v58, v42
	s_waitcnt vmcnt(14)
	v_xor_b32_e32 v54, v52, v53
	v_ashrrev_i32_e32 v54, 31, v54
	v_ffbh_i32_e32 v55, v53
	v_add_u32_e32 v54, 32, v54
	v_add_u32_e32 v55, -1, v55
	v_min_u32_e32 v54, v55, v54
	v_lshlrev_b64 v[52:53], v54, v[52:53]
	v_min_u32_e32 v52, 1, v52
	v_or_b32_e32 v52, v53, v52
	v_sub_u32_e32 v53, 32, v54
	v_lshlrev_b64 v[54:55], 8, v[50:51]
	v_lshl_add_u64 v[54:55], s[10:11], 0, v[54:55]
	v_lshl_add_u64 v[62:63], v[54:55], 0, v[0:1]
	v_mov_b64_e32 v[54:55], v[214:215]
	v_mov_b64_e32 v[56:57], v[216:217]
	v_cvt_f32_i32_e32 v52, v52
	v_ldexp_f32 v52, v52, v53
	v_mul_f32_e32 v52, 0x35800000, v52
	v_fmamk_f32 v52, v52, 0x3b000000, v180
	v_cmp_gt_f32_e32 vcc, s73, v52
	v_mul_f32_e32 v53, 0x4b800000, v52
	s_nop 0
	v_cndmask_b32_e32 v52, v52, v53, vcc
	v_rsq_f32_e32 v52, v52
	s_nop 0
	v_mul_f32_e32 v53, 0x45800000, v52
	v_cndmask_b32_e32 v52, v52, v53, vcc
	v_pk_mul_f32 v[58:59], v[58:59], v[52:53] op_sel_hi:[1,0]
	v_pk_mul_f32 v[60:61], v[54:55], v[58:59]
	s_nop 0
	v_sub_f32_e32 v53, v60, v61
	v_pk_mul_f32 v[54:55], v[54:55], v[58:59] op_sel:[0,1] op_sel_hi:[1,0]
	v_mov_b64_e32 v[58:59], v[222:223]
	v_mov_b64_e32 v[60:61], v[224:225]
	v_add_f32_e32 v42, v54, v55
	v_mov_b32_e32 v54, v34
	v_mov_b32_e32 v55, v38
	v_pk_mul_f32 v[64:65], v[54:55], v[52:53] op_sel_hi:[1,0]
	v_pk_mul_f32 v[46:47], v[46:47], v[52:53] op_sel_hi:[1,0]
	v_mov_b32_e32 v38, v35
	v_pk_mul_f32 v[38:39], v[38:39], v[52:53] op_sel_hi:[1,0]
	v_pk_mul_f32 v[54:55], v[58:59], v[64:65]
	v_pk_mul_f32 v[58:59], v[58:59], v[64:65] op_sel:[0,1] op_sel_hi:[1,0]
	v_sub_f32_e32 v54, v54, v55
	v_add_f32_e32 v34, v58, v59
	v_pk_mul_f32 v[58:59], v[56:57], v[46:47]
	v_pk_mul_f32 v[46:47], v[56:57], v[46:47] op_sel:[0,1] op_sel_hi:[1,0]
	v_sub_f32_e32 v43, v58, v59
	v_mov_b64_e32 v[56:57], v[218:219]
	v_mov_b64_e32 v[58:59], v[220:221]
	v_add_f32_e32 v55, v46, v47
	v_pk_mul_f32 v[46:47], v[60:61], v[38:39]
	v_pk_mul_f32 v[38:39], v[60:61], v[38:39] op_sel:[0,1] op_sel_hi:[1,0]
	v_mov_b64_e32 v[60:61], v[226:227]
	v_mov_b64_e32 v[62:63], v[228:229]
	v_add_f32_e32 v64, v38, v39
	v_mov_b32_e32 v38, v44
	v_mov_b32_e32 v39, v48
	v_pk_mul_f32 v[38:39], v[38:39], v[52:53] op_sel_hi:[1,0]
	v_sub_f32_e32 v35, v46, v47
	v_mov_b32_e32 v48, v45
	v_pk_mul_f32 v[46:47], v[56:57], v[38:39]
	v_pk_mul_f32 v[38:39], v[38:39], v[56:57] op_sel:[1,0] op_sel_hi:[0,1]
	v_add_f32_e32 v56, v38, v39
	v_mov_b32_e32 v38, v36
	v_mov_b32_e32 v39, v40
	v_pk_mul_f32 v[38:39], v[38:39], v[52:53] op_sel_hi:[1,0]
	v_sub_f32_e32 v65, v46, v47
	v_pk_mul_f32 v[46:47], v[38:39], v[60:61]
	v_pk_mul_f32 v[38:39], v[38:39], v[60:61] op_sel:[1,0] op_sel_hi:[0,1]
	v_sub_f32_e32 v46, v46, v47
	v_add_f32_e32 v47, v38, v39
	v_pk_mul_f32 v[38:39], v[48:49], v[52:53] op_sel_hi:[1,0]
	v_mov_b32_e32 v40, v37
	v_pk_mul_f32 v[44:45], v[38:39], v[58:59]
	v_pk_mul_f32 v[38:39], v[38:39], v[58:59] op_sel:[1,0] op_sel_hi:[0,1]
	v_pk_mul_f32 v[36:37], v[40:41], v[52:53] op_sel_hi:[1,0]
	v_sub_f32_e32 v44, v44, v45
	v_add_f32_e32 v45, v38, v39
	v_pk_mul_f32 v[38:39], v[36:37], v[62:63]
	v_pk_mul_f32 v[36:37], v[36:37], v[62:63] op_sel:[1,0] op_sel_hi:[0,1]
	v_add_f32_e32 v48, v36, v37
	v_lshlrev_b64 v[36:37], 11, v[50:51]
	v_sub_f32_e32 v39, v38, v39
	v_lshl_add_u64 v[36:37], s[20:21], 0, v[36:37]
	v_lshl_add_u64 v[40:41], v[36:37], 0, v[114:115]
	v_cvt_pk_bf16_f32 v36, v53, v43
	v_cvt_pk_bf16_f32 v37, v65, v44
	v_cvt_pk_bf16_f32 v38, v54, v35
	v_cvt_pk_bf16_f32 v39, v46, v39
	flat_store_dwordx4 v[40:41], v[36:39]
	v_mov_b32_e32 v43, v30
	v_mov_b32_e32 v30, v27
	v_cvt_pk_bf16_f32 v36, v42, v55
	v_cvt_pk_bf16_f32 v37, v56, v45
	v_cvt_pk_bf16_f32 v38, v34, v64
	v_cvt_pk_bf16_f32 v39, v47, v48
	flat_store_dwordx4 v[40:41], v[36:39] offset:64
	s_nop 1
	v_mov_b64_e32 v[36:37], v[174:175]
	v_add_u32_e32 v34, 0xa0, v130
	v_ashrrev_i32_e32 v35, 31, v34
	v_mov_b32_e32 v42, v26
	s_waitcnt vmcnt(10)
	v_xor_b32_e32 v38, v36, v37
	v_ashrrev_i32_e32 v38, 31, v38
	v_ffbh_i32_e32 v39, v37
	v_add_u32_e32 v38, 32, v38
	v_add_u32_e32 v39, -1, v39
	v_min_u32_e32 v38, v39, v38
	v_lshlrev_b64 v[36:37], v38, v[36:37]
	v_min_u32_e32 v36, 1, v36
	v_or_b32_e32 v36, v37, v36
	v_sub_u32_e32 v37, 32, v38
	v_lshlrev_b64 v[38:39], 8, v[34:35]
	v_lshl_add_u64 v[38:39], s[10:11], 0, v[38:39]
	v_lshl_add_u64 v[46:47], v[38:39], 0, v[0:1]
	v_mov_b64_e32 v[38:39], v[182:183]
	v_mov_b64_e32 v[40:41], v[184:185]
	v_cvt_f32_i32_e32 v36, v36
	v_ldexp_f32 v36, v36, v37
	v_mul_f32_e32 v36, 0x35800000, v36
	v_fmamk_f32 v36, v36, 0x3b000000, v180
	v_cmp_gt_f32_e32 vcc, s73, v36
	v_mul_f32_e32 v37, 0x4b800000, v36
	s_nop 0
	v_cndmask_b32_e32 v36, v36, v37, vcc
	v_rsq_f32_e32 v36, v36
	s_nop 0
	v_mul_f32_e32 v37, 0x45800000, v36
	v_cndmask_b32_e32 v36, v36, v37, vcc
	v_pk_mul_f32 v[42:43], v[42:43], v[36:37] op_sel_hi:[1,0]
	v_pk_mul_f32 v[44:45], v[38:39], v[42:43]
	s_nop 0
	v_sub_f32_e32 v37, v44, v45
	v_pk_mul_f32 v[38:39], v[38:39], v[42:43] op_sel:[0,1] op_sel_hi:[1,0]
	v_mov_b64_e32 v[42:43], v[190:191]
	v_mov_b64_e32 v[44:45], v[192:193]
	v_add_f32_e32 v26, v38, v39
	v_mov_b32_e32 v38, v18
	v_mov_b32_e32 v39, v22
	v_pk_mul_f32 v[48:49], v[38:39], v[36:37] op_sel_hi:[1,0]
	v_pk_mul_f32 v[30:31], v[30:31], v[36:37] op_sel_hi:[1,0]
	v_mov_b32_e32 v22, v19
	v_pk_mul_f32 v[22:23], v[22:23], v[36:37] op_sel_hi:[1,0]
	v_pk_mul_f32 v[38:39], v[42:43], v[48:49]
	v_pk_mul_f32 v[42:43], v[42:43], v[48:49] op_sel:[0,1] op_sel_hi:[1,0]
	v_sub_f32_e32 v38, v38, v39
	v_add_f32_e32 v18, v42, v43
	v_pk_mul_f32 v[42:43], v[40:41], v[30:31]
	v_pk_mul_f32 v[30:31], v[40:41], v[30:31] op_sel:[0,1] op_sel_hi:[1,0]
	v_sub_f32_e32 v27, v42, v43
	v_mov_b64_e32 v[40:41], v[186:187]
	v_mov_b64_e32 v[42:43], v[188:189]
	v_add_f32_e32 v39, v30, v31
	v_pk_mul_f32 v[30:31], v[44:45], v[22:23]
	v_pk_mul_f32 v[22:23], v[44:45], v[22:23] op_sel:[0,1] op_sel_hi:[1,0]
	v_mov_b64_e32 v[44:45], v[194:195]
	v_mov_b64_e32 v[46:47], v[196:197]
	v_add_f32_e32 v48, v22, v23
	v_mov_b32_e32 v22, v28
	v_mov_b32_e32 v23, v32
	v_pk_mul_f32 v[22:23], v[22:23], v[36:37] op_sel_hi:[1,0]
	v_sub_f32_e32 v19, v30, v31
	v_mov_b32_e32 v32, v29
	v_pk_mul_f32 v[30:31], v[40:41], v[22:23]
	v_pk_mul_f32 v[22:23], v[22:23], v[40:41] op_sel:[1,0] op_sel_hi:[0,1]
	v_add_f32_e32 v40, v22, v23
	v_mov_b32_e32 v22, v20
	v_mov_b32_e32 v23, v24
	v_pk_mul_f32 v[22:23], v[22:23], v[36:37] op_sel_hi:[1,0]
	v_sub_f32_e32 v49, v30, v31
	v_pk_mul_f32 v[30:31], v[22:23], v[44:45]
	v_pk_mul_f32 v[22:23], v[22:23], v[44:45] op_sel:[1,0] op_sel_hi:[0,1]
	v_sub_f32_e32 v30, v30, v31
	v_add_f32_e32 v31, v22, v23
	v_pk_mul_f32 v[22:23], v[32:33], v[36:37] op_sel_hi:[1,0]
	v_mov_b32_e32 v24, v21
	v_pk_mul_f32 v[28:29], v[22:23], v[42:43]
	v_pk_mul_f32 v[22:23], v[22:23], v[42:43] op_sel:[1,0] op_sel_hi:[0,1]
	v_pk_mul_f32 v[20:21], v[24:25], v[36:37] op_sel_hi:[1,0]
	v_sub_f32_e32 v28, v28, v29
	v_add_f32_e32 v29, v22, v23
	v_pk_mul_f32 v[22:23], v[20:21], v[46:47]
	v_pk_mul_f32 v[20:21], v[20:21], v[46:47] op_sel:[1,0] op_sel_hi:[0,1]
	v_add_f32_e32 v32, v20, v21
	v_lshlrev_b64 v[20:21], 11, v[34:35]
	v_sub_f32_e32 v23, v22, v23
	v_lshl_add_u64 v[20:21], s[20:21], 0, v[20:21]
	v_lshl_add_u64 v[24:25], v[20:21], 0, v[114:115]
	v_cvt_pk_bf16_f32 v20, v37, v27
	v_cvt_pk_bf16_f32 v21, v49, v28
	v_cvt_pk_bf16_f32 v22, v38, v19
	v_cvt_pk_bf16_f32 v23, v30, v23
	flat_store_dwordx4 v[24:25], v[20:23]
	v_mov_b32_e32 v27, v14
	v_mov_b32_e32 v14, v11
	v_cvt_pk_bf16_f32 v20, v26, v39
	v_cvt_pk_bf16_f32 v21, v40, v29
	v_cvt_pk_bf16_f32 v22, v18, v48
	v_cvt_pk_bf16_f32 v23, v31, v32
	flat_store_dwordx4 v[24:25], v[20:23] offset:64
	s_nop 1
	v_mov_b64_e32 v[20:21], v[176:177]
	v_add_u32_e32 v18, 0xb0, v130
	v_ashrrev_i32_e32 v19, 31, v18
	v_mov_b32_e32 v26, v10
	s_waitcnt vmcnt(6)
	v_xor_b32_e32 v22, v20, v21
	v_ashrrev_i32_e32 v22, 31, v22
	v_ffbh_i32_e32 v23, v21
	v_add_u32_e32 v22, 32, v22
	v_add_u32_e32 v23, -1, v23
	v_min_u32_e32 v22, v23, v22
	v_lshlrev_b64 v[20:21], v22, v[20:21]
	v_min_u32_e32 v20, 1, v20
	v_or_b32_e32 v20, v21, v20
	v_sub_u32_e32 v21, 32, v22
	v_lshlrev_b64 v[22:23], 8, v[18:19]
	v_lshl_add_u64 v[22:23], s[10:11], 0, v[22:23]
	v_lshl_add_u64 v[30:31], v[22:23], 0, v[0:1]
	v_mov_b64_e32 v[22:23], v[198:199]
	v_mov_b64_e32 v[24:25], v[200:201]
	v_cvt_f32_i32_e32 v20, v20
	v_ldexp_f32 v20, v20, v21
	v_mul_f32_e32 v20, 0x35800000, v20
	v_fmamk_f32 v20, v20, 0x3b000000, v180
	v_cmp_gt_f32_e32 vcc, s73, v20
	v_mul_f32_e32 v21, 0x4b800000, v20
	s_nop 0
	v_cndmask_b32_e32 v20, v20, v21, vcc
	v_rsq_f32_e32 v20, v20
	s_nop 0
	v_mul_f32_e32 v21, 0x45800000, v20
	v_cndmask_b32_e32 v20, v20, v21, vcc
	v_pk_mul_f32 v[26:27], v[26:27], v[20:21] op_sel_hi:[1,0]
	v_pk_mul_f32 v[28:29], v[22:23], v[26:27]
	s_nop 0
	v_sub_f32_e32 v10, v28, v29
	v_pk_mul_f32 v[22:23], v[22:23], v[26:27] op_sel:[0,1] op_sel_hi:[1,0]
	v_mov_b64_e32 v[26:27], v[206:207]
	v_mov_b64_e32 v[28:29], v[208:209]
	v_add_f32_e32 v0, v22, v23
	v_mov_b32_e32 v22, v2
	v_mov_b32_e32 v23, v6
	v_pk_mul_f32 v[22:23], v[22:23], v[20:21] op_sel_hi:[1,0]
	v_mov_b32_e32 v6, v3
	v_pk_mul_f32 v[32:33], v[26:27], v[22:23]
	s_nop 0
	v_sub_f32_e32 v21, v32, v33
	v_pk_mul_f32 v[22:23], v[26:27], v[22:23] op_sel:[0,1] op_sel_hi:[1,0]
	v_pk_mul_f32 v[14:15], v[14:15], v[20:21] op_sel_hi:[1,0]
	v_add_f32_e32 v2, v22, v23
	v_pk_mul_f32 v[22:23], v[24:25], v[14:15]
	v_pk_mul_f32 v[14:15], v[24:25], v[14:15] op_sel:[0,1] op_sel_hi:[1,0]
	v_sub_f32_e32 v11, v22, v23
	v_mov_b64_e32 v[22:23], v[202:203]
	v_mov_b64_e32 v[24:25], v[204:205]
	v_pk_mul_f32 v[6:7], v[6:7], v[20:21] op_sel_hi:[1,0]
	v_add_f32_e32 v32, v14, v15
	v_pk_mul_f32 v[14:15], v[28:29], v[6:7]
	v_pk_mul_f32 v[6:7], v[28:29], v[6:7] op_sel:[0,1] op_sel_hi:[1,0]
	v_mov_b64_e32 v[26:27], v[210:211]
	v_mov_b64_e32 v[28:29], v[212:213]
	v_add_f32_e32 v33, v6, v7
	v_mov_b32_e32 v6, v12
	v_mov_b32_e32 v7, v16
	v_pk_mul_f32 v[6:7], v[6:7], v[20:21] op_sel_hi:[1,0]
	v_sub_f32_e32 v3, v14, v15
	v_mov_b32_e32 v16, v13
	v_pk_mul_f32 v[14:15], v[22:23], v[6:7]
	v_pk_mul_f32 v[6:7], v[6:7], v[22:23] op_sel:[1,0] op_sel_hi:[0,1]
	v_add_f32_e32 v22, v6, v7
	v_mov_b32_e32 v6, v4
	v_mov_b32_e32 v7, v8
	v_pk_mul_f32 v[6:7], v[6:7], v[20:21] op_sel_hi:[1,0]
	v_sub_f32_e32 v34, v14, v15
	v_pk_mul_f32 v[14:15], v[6:7], v[26:27]
	v_pk_mul_f32 v[6:7], v[6:7], v[26:27] op_sel:[1,0] op_sel_hi:[0,1]
	v_sub_f32_e32 v14, v14, v15
	v_add_f32_e32 v15, v6, v7
	v_pk_mul_f32 v[6:7], v[16:17], v[20:21] op_sel_hi:[1,0]
	v_mov_b32_e32 v8, v5
	v_pk_mul_f32 v[12:13], v[6:7], v[24:25]
	v_pk_mul_f32 v[6:7], v[6:7], v[24:25] op_sel:[1,0] op_sel_hi:[0,1]
	v_pk_mul_f32 v[4:5], v[8:9], v[20:21] op_sel_hi:[1,0]
	v_sub_f32_e32 v12, v12, v13
	v_add_f32_e32 v13, v6, v7
	v_pk_mul_f32 v[6:7], v[4:5], v[28:29]
	v_pk_mul_f32 v[4:5], v[4:5], v[28:29] op_sel:[1,0] op_sel_hi:[0,1]
	v_add_f32_e32 v16, v4, v5
	v_lshlrev_b64 v[4:5], 11, v[18:19]
	v_sub_f32_e32 v7, v6, v7
	v_lshl_add_u64 v[4:5], s[20:21], 0, v[4:5]
	v_lshl_add_u64 v[8:9], v[4:5], 0, v[114:115]
	v_cvt_pk_bf16_f32 v4, v10, v11
	v_cvt_pk_bf16_f32 v5, v34, v12
	v_cvt_pk_bf16_f32 v6, v21, v3
	v_cvt_pk_bf16_f32 v7, v14, v7
	flat_store_dwordx4 v[8:9], v[4:7]
	s_nop 1
	v_cvt_pk_bf16_f32 v4, v0, v32
	v_cvt_pk_bf16_f32 v5, v22, v13
	v_cvt_pk_bf16_f32 v6, v2, v33
	v_cvt_pk_bf16_f32 v7, v15, v16
	flat_store_dwordx4 v[8:9], v[4:7] offset:64
	s_andn2_b64 vcc, exec, s[4:5]
	s_mov_b64 s[4:5], -1
	s_cbranch_vccnz .LBB0_538

	.amdhsa_kernel _Z10fwd_kernel4Args
		.amdhsa_group_segment_fixed_size 0
		.amdhsa_private_segment_fixed_size 0
		.amdhsa_kernarg_size 480
		.amdhsa_user_sgpr_count 2
		.amdhsa_user_sgpr_dispatch_ptr 0
		.amdhsa_user_sgpr_queue_ptr 0
		.amdhsa_user_sgpr_kernarg_segment_ptr 1
		.amdhsa_user_sgpr_dispatch_id 0
		.amdhsa_user_sgpr_kernarg_preload_length 0
		.amdhsa_user_sgpr_kernarg_preload_offset 0
		.amdhsa_user_sgpr_private_segment_size 0
		.amdhsa_uses_dynamic_stack 0
		.amdhsa_enable_private_segment 0
		.amdhsa_system_sgpr_workgroup_id_x 1
		.amdhsa_system_sgpr_workgroup_id_y 0
		.amdhsa_system_sgpr_workgroup_id_z 0
		.amdhsa_system_sgpr_workgroup_info 0
		.amdhsa_system_vgpr_workitem_id 0
		.amdhsa_next_free_vgpr 256
		.amdhsa_next_free_sgpr 102
		.amdhsa_accum_offset 256
		.amdhsa_reserve_vcc 1
		.amdhsa_float_round_mode_32 0
		.amdhsa_float_round_mode_16_64 0
		.amdhsa_float_denorm_mode_32 3
		.amdhsa_float_denorm_mode_16_64 3
		.amdhsa_dx10_clamp 1
		.amdhsa_ieee_mode 1
		.amdhsa_fp16_overflow 0
		.amdhsa_tg_split 0
		.amdhsa_exception_fp_ieee_invalid_op 0
		.amdhsa_exception_fp_denorm_src 0
		.amdhsa_exception_fp_ieee_div_zero 0
		.amdhsa_exception_fp_ieee_overflow 0
		.amdhsa_exception_fp_ieee_underflow 0
		.amdhsa_exception_fp_ieee_inexact 0
		.amdhsa_exception_int_div_zero 0
	.end_amdhsa_kernel

amdhsa.kernels:
  - .agpr_count:     0
    .args:
      - .offset:         0
        .size:           224
        .value_kind:     by_value
      - .offset:         224
        .size:           4
        .value_kind:     hidden_block_count_x
      - .offset:         228
        .size:           4
        .value_kind:     hidden_block_count_y
      - .offset:         232
        .size:           4
        .value_kind:     hidden_block_count_z
      - .offset:         236
        .size:           2
        .value_kind:     hidden_group_size_x
      - .offset:         238
        .size:           2
        .value_kind:     hidden_group_size_y
      - .offset:         240
        .size:           2
        .value_kind:     hidden_group_size_z
      - .offset:         242
        .size:           2
        .value_kind:     hidden_remainder_x
      - .offset:         244
        .size:           2
        .value_kind:     hidden_remainder_y
      - .offset:         246
        .size:           2
        .value_kind:     hidden_remainder_z
      - .offset:         264
        .size:           8
        .value_kind:     hidden_global_offset_x
      - .offset:         272
        .size:           8
        .value_kind:     hidden_global_offset_y
      - .offset:         280
        .size:           8
        .value_kind:     hidden_global_offset_z
      - .offset:         288
        .size:           2
        .value_kind:     hidden_grid_dims
      - .offset:         344
        .size:           4
        .value_kind:     hidden_dynamic_lds_size
    .group_segment_fixed_size: 0
    .kernarg_segment_align: 8
    .kernarg_segment_size: 480
    .language:       OpenCL C
    .language_version:
      - 2
      - 0
    .max_flat_workgroup_size: 512
    .name:           _Z10fwd_kernel4Args
    .private_segment_fixed_size: 0
    .sgpr_count:     108
    .sgpr_spill_count: 669
    .symbol:         _Z10fwd_kernel4Args.kd
    .uniform_work_group_size: 1
    .uses_dynamic_stack: false
    .vgpr_count:     256
    .vgpr_spill_count: 0
    .wavefront_size: 64
